# v109 with the E2 readiness poll moved off the ticket path: every wave loads its row-block counter at tile start (overlaps the prologue loads) and checks it before the first H load
# speedup vs baseline: 1.0117x; 1.0117x over previous
; template <class F>
; __device__ __forceinline__ void xcd_queue_run(unsigned* qwords, int nper, char* smem_aux, F fn) {
;     ...
;       if (threadIdx.x == 0) *slot = (int)__hip_atomic_fetch_add(qwords + 64 * j, 1u, __ATOMIC_RELAXED, __HIP_MEMORY_SCOPE_AGENT);
;       __syncthreads();
;       const int q = *slot;
;       if (q >= nper) break;
; __device__ void phaseE2(const Params& p, char* smem) {
;     ...
;   xcd_queue_run(p.bar + QW_BASE + 1536, s_rb[NEXP], smem + 2 * GEMM_SMEM + 800, [&](int j, int q) {
;     const int rbg = q, nt = j;
;     int e = 0;
;     while (s_rb[e + 1] <= rbg) e++;
;     const int rb = rbg - s_rb[e];
;     const int cnt = p.cnt[e];
;     const int rows = min(128, cnt - rb * 128);
;     const int slot0 = s_off[e] + rb * 128;
;     const int n0 = nt * 128;
;     const float* wd = p.w_down + (size_t)e * DEXP * DM;
;     const float* lg = p.list_gate + e * CAP + rb * 128;
;     auto rowf = [&](int r) { int rr = r < rows ? r : 0; return (const void*)(p.H + (size_t)(slot0 + rr) * DEXP); };
.LBB0_1355:
	s_or_b64 exec, exec, s[16:17]
	s_cmp_lg_u32 s33, -1
	s_cselect_b32 s2, s33, 0
	s_cselect_b32 s16, s1, 0
	v_mov_b32_e32 v0, s2
	v_mov_b32_e32 v1, s16
	s_waitcnt lgkmcnt(0)
	s_barrier
	flat_load_dword v2, v[0:1] sc0 sc1
	s_waitcnt vmcnt(0)
	s_mov_b64 s[18:19], -1
	s_waitcnt lgkmcnt(0)
	v_cmp_lt_i32_e32 vcc, v2, v108
	s_and_saveexec_b64 s[16:17], vcc
	s_cbranch_execz .LBB0_1350
	v_lshrrev_b32_e32 v236, 5, v2
	v_lshlrev_b32_e32 v236, 8, v236
	v_and_b32_e32 v237, 31, v2
	v_lshl_add_u32 v236, v237, 2, v236
	v_add_u32_e32 v236, 0x4604, v236
	global_load_dword v237, v236, s[82:83] sc1
	s_mov_b64 s[18:19], 0
	v_mbcnt_lo_u32_b32 v3, -1, 0
	v_mbcnt_hi_u32_b32 v3, -1, v3
	v_lshl_add_u32 v3, v3, 2, s24
	ds_read_b32 v3, v3
	s_waitcnt lgkmcnt(0)
	v_cmp_le_i32_e32 vcc, v3, v2
	s_bcnt1_i32_b64 s2, vcc
	v_mov_b32_e32 v80, s2
	s_lshl_b32 s20, s2, 21
	s_mov_b32 s21, 0
	v_lshl_add_u64 v[96:97], v[90:91], 0, s[20:21]
	s_or_b64 exec, exec, s[18:19]
	v_mul_u32_u24_e32 v0, 0x20100, v80
	v_mov_b32_e32 v1, 0
	v_lshl_add_u64 v[0:1], v[0:1], 0, s[62:63]
	global_load_dword v3, v[0:1], off
	v_lshl_add_u32 v4, v80, 2, 0
	v_lshlrev_b64 v[0:1], 21, v[80:81]
	v_add_u32_e32 v5, 0x10120, v4
	v_add_u32_e32 v4, 0x10000, v4
	v_lshl_add_u64 v[0:1], v[92:93], 0, v[0:1]
	ds_read_b32 v22, v5
	ds_read_b32 v23, v4
	v_add_co_u32_e32 v4, vcc, s26, v0
	v_mov_b32_e32 v64, 0
	s_nop 0
	v_addc_co_u32_e32 v5, vcc, 0, v1, vcc
	v_add_co_u32_e32 v6, vcc, s27, v0
	s_waitcnt lgkmcnt(1)
	v_sub_u32_e32 v2, v2, v22
	v_addc_co_u32_e32 v7, vcc, 0, v1, vcc
	v_add_co_u32_e32 v8, vcc, s28, v0
	v_lshlrev_b32_e32 v98, 7, v2
	s_nop 0
	v_addc_co_u32_e32 v9, vcc, 0, v1, vcc
	v_add_co_u32_e32 v10, vcc, s29, v0
	s_waitcnt lgkmcnt(0)
	v_add_u32_e32 v117, v23, v98
	v_addc_co_u32_e32 v11, vcc, 0, v1, vcc
	v_add_co_u32_e32 v12, vcc, s30, v0
	s_mov_b32 s2, 0
	s_nop 0
	v_addc_co_u32_e32 v13, vcc, 0, v1, vcc
	v_add_co_u32_e32 v14, vcc, s31, v0
	s_mov_b32 s47, 0
	s_nop 0
	v_addc_co_u32_e32 v15, vcc, 0, v1, vcc
	v_add_co_u32_e32 v16, vcc, s36, v0
	v_mov_b32_e32 v65, v64
	s_nop 0
	v_addc_co_u32_e32 v17, vcc, 0, v1, vcc
	v_add_co_u32_e32 v18, vcc, s25, v0
	global_load_dword v141, v[0:1], off
	global_load_dword v99, v[4:5], off offset:-4096
	global_load_dword v119, v[4:5], off
	global_load_dword v120, v[6:7], off offset:-4096
	global_load_dword v121, v[6:7], off
	global_load_dword v122, v[8:9], off offset:-4096
	global_load_dword v123, v[8:9], off
	global_load_dword v128, v[10:11], off offset:-4096
	global_load_dword v130, v[10:11], off
	global_load_dword v132, v[12:13], off offset:-4096
	global_load_dword v133, v[12:13], off
	global_load_dword v134, v[14:15], off offset:-4096
	global_load_dword v135, v[14:15], off
	global_load_dword v136, v[16:17], off offset:-4096
	global_load_dword v137, v[16:17], off
	v_addc_co_u32_e32 v19, vcc, 0, v1, vcc
	v_add_co_u32_e32 v20, vcc, s37, v0
	v_mov_b32_e32 v66, v64
	s_nop 0
	v_addc_co_u32_e32 v21, vcc, 0, v1, vcc
	v_mov_b32_e32 v67, v64
	v_mov_b32_e32 v76, v64
	v_mov_b32_e32 v77, v64
	v_mov_b32_e32 v78, v64
	v_mov_b32_e32 v79, v64
	v_mov_b32_e32 v72, v64
	v_mov_b32_e32 v73, v64
	v_mov_b32_e32 v74, v64
	v_mov_b32_e32 v75, v64
	v_mov_b32_e32 v68, v64
	v_mov_b32_e32 v69, v64
	v_mov_b32_e32 v70, v64
	v_mov_b32_e32 v71, v64
	v_mov_b32_e32 v60, v64
	v_mov_b32_e32 v61, v64
	v_mov_b32_e32 v62, v64
	v_mov_b32_e32 v63, v64
	v_mov_b32_e32 v56, v64
	v_mov_b32_e32 v57, v64
	v_mov_b32_e32 v58, v64
	v_mov_b32_e32 v59, v64
	v_mov_b32_e32 v52, v64
	v_mov_b32_e32 v53, v64
	v_mov_b32_e32 v54, v64
	v_mov_b32_e32 v55, v64
	v_mov_b32_e32 v48, v64
	v_mov_b32_e32 v49, v64
	v_mov_b32_e32 v50, v64
	s_waitcnt vmcnt(15)
	v_sub_u32_e32 v2, v3, v98
	v_min_i32_e32 v118, 0x80, v2
	v_cmp_lt_i32_e32 vcc, v160, v118
	v_mov_b32_e32 v51, v64
	v_mov_b32_e32 v28, v64
	v_cndmask_b32_e32 v2, 0, v160, vcc
	v_cmp_lt_i32_e32 vcc, v150, v118
	v_add_u32_e32 v2, v2, v117
	v_mov_b32_e32 v29, v64
	v_cndmask_b32_e32 v3, 0, v150, vcc
	v_cmp_lt_i32_e32 vcc, v151, v118
	v_add_u32_e32 v4, v3, v117
	v_ashrrev_i32_e32 v3, 31, v2
	v_cndmask_b32_e32 v5, 0, v151, vcc
	v_cmp_lt_i32_e32 vcc, v152, v118
	v_add_u32_e32 v6, v5, v117
	v_ashrrev_i32_e32 v5, 31, v4
	v_cndmask_b32_e32 v7, 0, v152, vcc
	v_add_co_u32_e32 v10, vcc, s38, v0
	v_add_u32_e32 v8, v7, v117
	s_nop 0
	v_addc_co_u32_e32 v11, vcc, 0, v1, vcc
	v_add_co_u32_e32 v12, vcc, s39, v0
	v_ashrrev_i32_e32 v7, 31, v6
	s_nop 0
	v_addc_co_u32_e32 v13, vcc, 0, v1, vcc
	global_load_dword v138, v[18:19], off offset:-4096
	global_load_dword v139, v[18:19], off
	global_load_dword v140, v[20:21], off offset:-4096
	global_load_dword v142, v[20:21], off
	global_load_dword v143, v[10:11], off offset:-4096
	global_load_dword v144, v[10:11], off
	global_load_dword v145, v[12:13], off offset:-4096
	global_load_dword v146, v[12:13], off
	v_add_co_u32_e32 v10, vcc, s40, v0
	v_lshlrev_b64 v[16:17], 10, v[2:3]
	s_nop 0
	v_addc_co_u32_e32 v11, vcc, 0, v1, vcc
	v_add_co_u32_e32 v12, vcc, s41, v0
	v_ashrrev_i32_e32 v9, 31, v8
	s_nop 0
	v_addc_co_u32_e32 v13, vcc, 0, v1, vcc
	v_add_co_u32_e32 v14, vcc, s42, v0
	v_lshlrev_b64 v[22:23], 10, v[4:5]
	s_nop 0
	v_addc_co_u32_e32 v15, vcc, 0, v1, vcc
	v_add_co_u32_e32 v18, vcc, s43, v0
	v_lshlrev_b64 v[24:25], 10, v[6:7]
	s_nop 0
	v_addc_co_u32_e32 v19, vcc, 0, v1, vcc
	v_add_co_u32_e32 v0, vcc, s44, v0
	v_lshl_add_u64 v[2:3], v[86:87], 0, v[16:17]
	s_nop 0
	v_addc_co_u32_e32 v1, vcc, 0, v1, vcc
	global_load_dword v147, v[10:11], off offset:-4096
	global_load_dword v153, v[10:11], off
	global_load_dword v154, v[12:13], off offset:-4096
	global_load_dword v155, v[12:13], off
	global_load_dword v156, v[14:15], off offset:-4096
	global_load_dword v157, v[14:15], off
	global_load_dword v158, v[18:19], off offset:-4096
	global_load_dword v159, v[18:19], off
	global_load_dword v170, v[0:1], off
	v_lshlrev_b64 v[18:19], 10, v[8:9]
	v_lshl_add_u64 v[4:5], v[86:87], 0, v[22:23]
	v_lshl_add_u64 v[6:7], v[86:87], 0, v[24:25]
	v_lshl_add_u64 v[0:1], v[86:87], 0, v[18:19]
	v_lshrrev_b32_e32 v46, 2, v149
	v_lshrrev_b32_e32 v35, 4, v46
	v_xor_b32_e32 v35, v35, v46
	v_and_b32_e32 v35, 7, v35
	v_lshlrev_b32_e32 v34, 4, v35
	v_mov_b32_e32 v35, 0
	v_sub_u32_e32 v38, v34, v124
	v_lshrrev_b32_e32 v46, 6, v46
	v_ashrrev_i32_e32 v39, 31, v38
	v_readfirstlane_b32 s100, v46
	s_lshl_b32 s100, s100, 10
	v_readfirstlane_b32 s98, v118
	s_lshr_b32 s99, s100, 11
	s_cmp_le_u32 s98, 64
	s_cselect_b32 s98, 1, 0
	s_and_b32 s99, s99, s98
	v_readfirstlane_b32 s49, v237
	s_cmp_ge_u32 s49, 8
	s_cbranch_scc1 .Le2_rdy
	s_mov_b32 s50, 0
; template <bool ABF, bool BBF, class RowF, class ColF, class Epi>
; __device__ __forceinline__ void gemm_tile(char* smem, int K, RowF rowptr, ColF colptr, int ldb, Epi epi) {
;     ...
;   auto gload = [&](int k0) {
; #pragma unroll
;     for (int i = 0; i < NA; i++) ra[i] = *(const u32x4*)(ap[i] + (size_t)k0 * (ABF ? 2 : 4));
;     if (BBF) {
; #pragma unroll
;       for (int i = 0; i < 4; i++) rbb[BBF ? i : 0] = *(const u32x4*)(bq[i] + (size_t)k0 * 2);
;     } else {
;       const float* b = bp + (size_t)k0 * ldb;
; #pragma unroll
;       for (int j = 0; j < 32; j++) rb[BBF ? 0 : j] = b[(size_t)j * ldb];
;     }
;   };
;   auto sstore = [&](int buf) {
;     u16* As = As0 + buf * (GEMM_SMEM / 2);
;     u16* Bs = As + BM * LDT;
; #pragma unroll
;     for (int i = 0; i < NA; i++) {
;       if (ABF) {
;         { const int row = ar0 + ARS * i; *(u32x4*)&As[row * LDT + (((ac >> 3) ^ ((row >> 1) & 7)) << 3)] = ra[i]; }
;       } else {
;         u32x2 v;
;         v[0] = pack2(__uint_as_float(ra[i][0]), __uint_as_float(ra[i][1]));
;         v[1] = pack2(__uint_as_float(ra[i][2]), __uint_as_float(ra[i][3]));
;         { const int row = ar0 + ARS * i; *(u32x2*)&As[row * LDT + (((ac >> 3) ^ ((row >> 1) & 7)) << 3) + (ac & 4)] = v; }
;       }
;     }
;     if (BBF) {
; #pragma unroll
;       for (int i = 0; i < 4; i++) { const int row = br0 + 32 * i; *(u32x4*)&Bs[row * LDT + (((bcc >> 3) ^ ((row >> 1) & 7)) << 3)] = rbb[BBF ? i : 0]; }
;     } else {
; #pragma unroll
;       for (int j = 0; j < 4; j++) {
;         u32x4 v;
;         v[0] = pack2(rb[BBF ? 0 : 8 * j + 0], rb[BBF ? 0 : 8 * j + 1]);
;         v[1] = pack2(rb[BBF ? 0 : 8 * j + 2], rb[BBF ? 0 : 8 * j + 3]);
;         v[2] = pack2(rb[BBF ? 0 : 8 * j + 4], rb[BBF ? 0 : 8 * j + 5]);
;         v[3] = pack2(rb[BBF ? 0 : 8 * j + 6], rb[BBF ? 0 : 8 * j + 7]);
;         *(u32x4*)&Bs[bc * LDT + (((kh * 4 + j) ^ ((bc >> 1) & 7)) << 3)] = v;
;       }
;     }
;   };
;   gload(0);
;   sstore(0);
;   __syncthreads();
.Le2_spin:
	global_load_dword v237, v236, s[82:83] sc1
	s_waitcnt vmcnt(0)
	v_readfirstlane_b32 s49, v237
	s_cmp_ge_u32 s49, 8
	s_cbranch_scc1 .Le2_rdy
	s_add_u32 s50, s50, 1
	s_sleep 1
	s_cmp_lt_u32 s50, 0x4000
	s_cbranch_scc1 .Le2_spin
.Le2_rdy:
	s_add_u32 m0, s100, 0x0
	v_lshl_add_u64 v[42:43], v[2:3], 0, v[38:39]
	global_load_lds_dwordx4 v[42:43], off
	s_add_u32 m0, s100, 0x1000
	v_lshl_add_u64 v[42:43], v[4:5], 0, v[38:39]
	global_load_lds_dwordx4 v[42:43], off
	s_add_u32 m0, s100, 0x2000
	v_lshl_add_u64 v[42:43], v[6:7], 0, v[38:39]
	global_load_lds_dwordx4 v[42:43], off
	s_add_u32 m0, s100, 0x3000
	v_lshl_add_u64 v[42:43], v[0:1], 0, v[38:39]
	global_load_lds_dwordx4 v[42:43], off
	s_waitcnt vmcnt(34)
	v_cvt_pk_bf16_f32 v0, v141, v99
	s_waitcnt vmcnt(32)
	v_cvt_pk_bf16_f32 v1, v119, v120
	s_waitcnt vmcnt(30)
	v_cvt_pk_bf16_f32 v2, v121, v122
	s_waitcnt vmcnt(28)
	v_cvt_pk_bf16_f32 v3, v123, v128
	s_waitcnt vmcnt(26)
	v_cvt_pk_bf16_f32 v4, v130, v132
	s_waitcnt vmcnt(24)
	v_cvt_pk_bf16_f32 v5, v133, v134
	s_waitcnt vmcnt(22)
	v_cvt_pk_bf16_f32 v6, v135, v136
	v_lshl_add_u64 v[100:101], s[8:9], 0, v[16:17]
	v_lshl_add_u64 v[102:103], s[8:9], 0, v[22:23]
	v_lshl_add_u64 v[104:105], s[8:9], 0, v[24:25]
	v_lshl_add_u64 v[106:107], s[8:9], 0, v[18:19]
	v_mov_b32_e32 v30, v64
	v_mov_b32_e32 v31, v64
	v_mov_b32_e32 v24, v64
	v_mov_b32_e32 v25, v64
	v_mov_b32_e32 v26, v64
	v_mov_b32_e32 v27, v64
	v_mov_b32_e32 v20, v64
	v_mov_b32_e32 v21, v64
	v_mov_b32_e32 v22, v64
	v_mov_b32_e32 v23, v64
	v_mov_b32_e32 v16, v64
	v_mov_b32_e32 v17, v64
	v_mov_b32_e32 v18, v64
	v_mov_b32_e32 v19, v64
	s_waitcnt vmcnt(20)
	v_cvt_pk_bf16_f32 v7, v137, v138
	s_waitcnt vmcnt(18)
	v_cvt_pk_bf16_f32 v8, v139, v140
	s_waitcnt vmcnt(16)
	v_cvt_pk_bf16_f32 v9, v142, v143
	s_waitcnt vmcnt(14)
	v_cvt_pk_bf16_f32 v10, v144, v145
	s_waitcnt vmcnt(12)
	v_cvt_pk_bf16_f32 v11, v146, v147
	s_waitcnt vmcnt(10)
	v_cvt_pk_bf16_f32 v12, v153, v154
	s_waitcnt vmcnt(8)
	v_cvt_pk_bf16_f32 v13, v155, v156
	s_waitcnt vmcnt(6)
	v_cvt_pk_bf16_f32 v14, v157, v158
	s_waitcnt vmcnt(4)
	v_cvt_pk_bf16_f32 v15, v159, v170
	s_waitcnt vmcnt(3)
	s_waitcnt vmcnt(2)
	s_waitcnt vmcnt(1)
	s_waitcnt vmcnt(0)
	ds_write_b128 v113, v[0:3] offset:16384
	ds_write_b128 v114, v[4:7] offset:16384
	ds_write_b128 v115, v[8:11] offset:16384
	ds_write_b128 v116, v[12:15] offset:16384
	v_mov_b32_e32 v12, v64
	v_mov_b32_e32 v13, v64
	v_mov_b32_e32 v14, v64
	v_mov_b32_e32 v15, v64
	v_mov_b32_e32 v8, v64
	v_mov_b32_e32 v9, v64
	v_mov_b32_e32 v10, v64
	v_mov_b32_e32 v11, v64
	v_mov_b32_e32 v4, v64
	v_mov_b32_e32 v5, v64
	v_mov_b32_e32 v6, v64
	v_mov_b32_e32 v7, v64
	v_mov_b32_e32 v0, v64
	v_mov_b32_e32 v1, v64
	v_mov_b32_e32 v2, v64
	v_mov_b32_e32 v3, v64
	s_waitcnt lgkmcnt(0)
	s_barrier
	s_branch .LBB0_1360
